# combined: barrier hop skip + NSA bias-read hoist + V-read move-up + 2nd-half K-read hoist + prefetch block before step barrier
# speedup vs baseline: 1.0052x; 1.0052x over previous
; template <int MODE>
; __device__ __forceinline__ void nsa_compute(int cur, int buf, int t, int hl, u64 mymask, const bf16x8 (&Qf)[2][2], f32x4 (&O)[4][2], float (&m)[2], float (&l)[2],
;                                             const float (&inv)[2], float* impw, char* lds) {
;     ...
;     for (int ks = 0; ks < 2; ++ks)
; #pragma unroll
;       for (int kk = 0; kk < 2; ++kk) kfr[ks][kk] = *(const bf16x8*)(kt + (32 * s2 + 16 * kk + fr) * 128 + (((ks * 4 + fq) ^ (fr & 7)) << 4));
;     __builtin_amdgcn_s_setprio(1);
; #pragma unroll
;     for (int ks = 0; ks < 2; ++ks)
; #pragma unroll
;       for (int kk = 0; kk < 2; ++kk)
; #pragma unroll
;         for (int r = 0; r < 2; ++r) S[kk][r] = mfma16(kfr[ks][kk], Qf[r][ks], S[kk][r]);
;     __builtin_amdgcn_s_setprio(0);
;     bf16x8 Pf[2];
;     float g1s[2] = {0.f, 0.f}, p3s[2] = {0.f, 0.f};
; #pragma unroll
;     for (int r = 0; r < 2; ++r) {
;       float sv[2][4];
; #pragma unroll
;       for (int kk = 0; kk < 2; ++kk)
; #pragma unroll
;         for (int e = 0; e < 4; ++e) {
;           const int off = 32 * s2 + 16 * kk + e;
;           int idx;
;           if (MODE <= 1) { idx = base - 16 * off; idx = idx > 0 ? idx : 0; } else idx = base - off;
;     ...
;           for (int e = 0; e < 4; ++e) { pv[kk][e] = __builtin_amdgcn_exp2f(sv[kk][e] - me); ps += pv[kk][e]; }
;         l[r] += ps;
;       }
;       if (MODE != 0) {
;         const unsigned w0 = pk2(pv[0][0], pv[0][1]), w1 = pk2(pv[0][2], pv[0][3]), w2 = pk2(pv[1][0], pv[1][1]), w3 = pk2(pv[1][2], pv[1][3]);
;         u32x4 pw; pw.x = w0; pw.y = w1; pw.z = w2; pw.w = w3;
;         Pf[r] = __builtin_bit_cast(bf16x8, pw);
;       }
;     }
;     if (MODE != 0) {
;       bf16x8 vfr[4];
; #pragma unroll
;       for (int df = 0; df < 4; ++df) {
;         const bf16x4 va = *(const bf16x4*)(vt + (df * 16 + fr) * 68 + 32 * s2 + 4 * fq);
;         const bf16x4 vb = *(const bf16x4*)(vt + (df * 16 + fr) * 68 + 32 * s2 + 16 + 4 * fq);
;         bf16x8 vf; vf[0] = va[0]; vf[1] = va[1]; vf[2] = va[2]; vf[3] = va[3]; vf[4] = vb[0]; vf[5] = vb[1]; vf[6] = vb[2]; vf[7] = vb[3];
;         vfr[df] = vf;
;       }
;       __builtin_amdgcn_s_setprio(1);
; #pragma unroll
;       for (int df = 0; df < 4; ++df)
; #pragma unroll
;         for (int r = 0; r < 2; ++r) O[df][r] = mfma16(vfr[df], Pf[r], O[df][r]);
;       __builtin_amdgcn_s_setprio(0);
.LBB0_367:
	v_sub_f32_e32 v75, v81, v74
	v_exp_f32_e32 v75, v75
	v_sub_f32_e32 v80, v80, v74
	v_exp_f32_e32 v80, v80
	v_sub_f32_e32 v78, v78, v74
	v_exp_f32_e32 v78, v78
	v_sub_f32_e32 v81, v82, v74
	v_exp_f32_e32 v81, v81
	v_sub_f32_e32 v77, v77, v74
	v_add_f32_e32 v79, 0, v75
	v_exp_f32_e32 v77, v77
	v_sub_f32_e32 v76, v76, v74
	v_add_f32_e32 v79, v80, v79
	v_exp_f32_e32 v76, v76
	v_sub_f32_e32 v73, v73, v74
	v_add_f32_e32 v79, v78, v79
	v_exp_f32_e32 v73, v73
	v_sub_f32_e32 v72, v72, v74
	v_add_f32_e32 v79, v81, v79
	v_exp_f32_e32 v72, v72
	v_add_f32_e32 v79, v77, v79
	v_add_f32_e32 v79, v76, v79
	v_add_f32_e32 v79, v73, v79
	v_add_f32_e32 v74, v72, v79
	v_cvt_pk_bf16_f32 v149, v73, v72
	v_cvt_pk_bf16_f32 v146, v75, v80
	v_add_f32_e32 v191, v191, v74
	v_cvt_pk_bf16_f32 v147, v78, v81
	v_cvt_pk_bf16_f32 v148, v77, v76
	v_cvt_pk_bf16_f32 v142, v85, v86
	v_cvt_pk_bf16_f32 v143, v87, v84
	v_cvt_pk_bf16_f32 v144, v89, v94
	v_cvt_pk_bf16_f32 v145, v95, v88
	v_add_u32_e32 v141, v91, v90
	v_add_u32_e32 v176, v100, v90
	ds_read_b128 v[206:209], v141 offset:4096
	ds_read_b128 v[236:239], v141 offset:6144
	ds_read_b128 v[240:243], v176 offset:4096
	ds_read_b128 v[244:247], v176 offset:6144
	s_setprio 1
	s_waitcnt lgkmcnt(7)
	v_mfma_f32_16x16x32_bf16 v[84:87], v[168:171], v[142:145], v[116:119]
	v_mfma_f32_16x16x32_bf16 v[96:99], v[168:171], v[146:149], v[104:107]
	s_waitcnt lgkmcnt(6)
	v_mfma_f32_16x16x32_bf16 v[80:83], v[200:203], v[142:145], v[124:127]
	v_mfma_f32_16x16x32_bf16 v[92:95], v[200:203], v[146:149], v[108:111]
	s_waitcnt lgkmcnt(5)
	v_mfma_f32_16x16x32_bf16 v[76:79], v[150:153], v[142:145], v[128:131]
	v_mfma_f32_16x16x32_bf16 v[108:111], v[150:153], v[146:149], v[112:115]
	s_waitcnt lgkmcnt(4)
	v_mfma_f32_16x16x32_bf16 v[72:75], v[154:157], v[142:145], v[132:135]
	v_mfma_f32_16x16x32_bf16 v[104:107], v[154:157], v[146:149], v[120:123]
	s_setprio 0
	v_add_u32_e32 v88, v91, v90
	v_add_u32_e32 v100, v100, v90
	v_add_u32_e32 v251, 0xa00, v136
	ds_read2_b32 v[168:169], v136 offset0:31 offset1:32
	ds_read2_b32 v[170:171], v136 offset0:29 offset1:30
	ds_read2_b32 v[172:173], v136 offset0:15 offset1:16
	ds_read2_b32 v[174:175], v136 offset0:13 offset1:14
	ds_read2_b32 v[198:199], v251 offset0:31 offset1:32
	ds_read2_b32 v[200:201], v251 offset0:29 offset1:30
	ds_read2_b32 v[202:203], v251 offset0:15 offset1:16
	ds_read2_b32 v[204:205], v251 offset0:13 offset1:14
	s_setprio 1
	s_waitcnt lgkmcnt(11)
	v_mfma_f32_16x16x32_bf16 v[100:103], v[206:209], v[0:3], 0
	v_mfma_f32_16x16x32_bf16 v[112:115], v[206:209], v[8:11], 0
	s_waitcnt lgkmcnt(10)
	v_mfma_f32_16x16x32_bf16 v[124:127], v[236:239], v[0:3], 0
	v_mfma_f32_16x16x32_bf16 v[116:119], v[236:239], v[8:11], 0
	s_waitcnt lgkmcnt(9)
	v_mfma_f32_16x16x32_bf16 v[128:131], v[240:243], v[4:7], v[100:103]
	v_mfma_f32_16x16x32_bf16 v[100:103], v[240:243], v[12:15], v[112:115]
	s_waitcnt lgkmcnt(8)
	v_mfma_f32_16x16x32_bf16 v[88:91], v[244:247], v[12:15], v[116:119]
	v_mfma_f32_16x16x32_bf16 v[124:127], v[244:247], v[4:7], v[124:127]
	s_setprio 0
	s_nop 0
	s_waitcnt lgkmcnt(7)
	s_nop 0
	v_fmamk_f32 v123, v128, 0x3e38aa3b, v169
	v_fmamk_f32 v118, v129, 0x3e38aa3b, v168
	s_waitcnt lgkmcnt(6)
	v_fmamk_f32 v122, v130, 0x3e38aa3b, v171
	v_fmamk_f32 v116, v131, 0x3e38aa3b, v170
	s_waitcnt lgkmcnt(5)
	v_fmamk_f32 v119, v124, 0x3e38aa3b, v173
	v_fmamk_f32 v114, v125, 0x3e38aa3b, v172
	s_waitcnt lgkmcnt(4)
	v_fmamk_f32 v113, v126, 0x3e38aa3b, v175
	v_fmamk_f32 v112, v127, 0x3e38aa3b, v174
	ds_read2_b64 v[168:171], v137 offset0:8 offset1:12
	ds_read2_b64 v[126:129], v138 offset0:24 offset1:28
	ds_read2_b64 v[130:133], v139 offset0:40 offset1:44
	ds_read2_b64 v[134:137], v140 offset0:56 offset1:60
	v_max3_f32 v115, v123, v118, v122
	v_max3_f32 v117, v116, v119, v114
	v_max_f32_e32 v120, v113, v112
	v_max3_f32 v115, v120, v115, v117
	v_add_f32_e32 v117, 0x41000000, v192
	v_cmp_gt_f32_e32 vcc, v115, v117
	s_cbranch_vccz .LBB0_369
	ds_bpermute_b32 v117, v233, v115
	v_max_f32_e32 v115, v115, v115
	v_mov_b32_e32 v121, v193
	s_waitcnt lgkmcnt(0)
	v_max_f32_e32 v117, v117, v117
	v_max_f32_e32 v115, v115, v117
	ds_bpermute_b32 v117, v234, v115
	s_waitcnt lgkmcnt(0)
	v_max3_f32 v120, v192, v115, v117
	v_sub_f32_e32 v115, v192, v120
	v_exp_f32_e32 v124, v115
	v_mov_b64_e32 v[192:193], v[120:121]
	v_mul_f32_e32 v190, v190, v124
	v_pk_mul_f32 v[86:87], v[86:87], v[124:125] op_sel_hi:[1,0]
	v_pk_mul_f32 v[84:85], v[84:85], v[124:125] op_sel_hi:[1,0]
	v_pk_mul_f32 v[82:83], v[82:83], v[124:125] op_sel_hi:[1,0]
	v_pk_mul_f32 v[80:81], v[80:81], v[124:125] op_sel_hi:[1,0]
	v_pk_mul_f32 v[78:79], v[78:79], v[124:125] op_sel_hi:[1,0]
	v_pk_mul_f32 v[76:77], v[76:77], v[124:125] op_sel_hi:[1,0]
	v_pk_mul_f32 v[74:75], v[74:75], v[124:125] op_sel_hi:[1,0]
	v_pk_mul_f32 v[72:73], v[72:73], v[124:125] op_sel_hi:[1,0]
	s_branch .LBB0_370

; template <int MODE>
; __device__ __forceinline__ void nsa_compute(int cur, int buf, int t, int hl, u64 mymask, const bf16x8 (&Qf)[2][2], f32x4 (&O)[4][2], float (&m)[2], float (&l)[2],
;                                             const float (&inv)[2], float* impw, char* lds) {
;     ...
; #pragma unroll
;     for (int ks = 0; ks < 2; ++ks)
; #pragma unroll
;       for (int kk = 0; kk < 2; ++kk) kfr[ks][kk] = *(const bf16x8*)(kt + (32 * s2 + 16 * kk + fr) * 128 + (((ks * 4 + fq) ^ (fr & 7)) << 4));
;     __builtin_amdgcn_s_setprio(1);
; #pragma unroll
;     for (int ks = 0; ks < 2; ++ks)
; #pragma unroll
;       for (int kk = 0; kk < 2; ++kk)
; #pragma unroll
;         for (int r = 0; r < 2; ++r) S[kk][r] = mfma16(kfr[ks][kk], Qf[r][ks], S[kk][r]);
;     __builtin_amdgcn_s_setprio(0);
;     bf16x8 Pf[2];
;     float g1s[2] = {0.f, 0.f}, p3s[2] = {0.f, 0.f};
; #pragma unroll
;     for (int r = 0; r < 2; ++r) {
;       float sv[2][4];
; #pragma unroll
;       for (int kk = 0; kk < 2; ++kk)
; #pragma unroll
;         for (int e = 0; e < 4; ++e) {
;     ...
;         const float me = (MODE == 2) ? (selok ? m[r] : __builtin_inff()) : m[r];
;         float ps = 0.f;
; #pragma unroll
;         for (int kk = 0; kk < 2; ++kk)
; #pragma unroll
;           for (int e = 0; e < 4; ++e) { pv[kk][e] = __builtin_amdgcn_exp2f(sv[kk][e] - me); ps += pv[kk][e]; }
;         l[r] += ps;
;       }
;       if (MODE != 0) {
;         const unsigned w0 = pk2(pv[0][0], pv[0][1]), w1 = pk2(pv[0][2], pv[0][3]), w2 = pk2(pv[1][0], pv[1][1]), w3 = pk2(pv[1][2], pv[1][3]);
;         u32x4 pw; pw.x = w0; pw.y = w1; pw.z = w2; pw.w = w3;
;         Pf[r] = __builtin_bit_cast(bf16x8, pw);
;       }
;     }
;     if (MODE != 0) {
;       bf16x8 vfr[4];
; #pragma unroll
;       for (int df = 0; df < 4; ++df) {
;         const bf16x4 va = *(const bf16x4*)(vt + (df * 16 + fr) * 68 + 32 * s2 + 4 * fq);
;         const bf16x4 vb = *(const bf16x4*)(vt + (df * 16 + fr) * 68 + 32 * s2 + 16 + 4 * fq);
;         bf16x8 vf; vf[0] = va[0]; vf[1] = va[1]; vf[2] = va[2]; vf[3] = va[3]; vf[4] = vb[0]; vf[5] = vb[1]; vf[6] = vb[2]; vf[7] = vb[3];
;         vfr[df] = vf;
;       }
;       __builtin_amdgcn_s_setprio(1);
; #pragma unroll
;       for (int df = 0; df < 4; ++df)
; #pragma unroll
;         for (int r = 0; r < 2; ++r) O[df][r] = mfma16(vfr[df], Pf[r], O[df][r]);
;       __builtin_amdgcn_s_setprio(0);
.LBB0_385:
	v_sub_f32_e32 v119, v135, v118
	v_exp_f32_e32 v119, v119
	v_sub_f32_e32 v134, v134, v118
	v_exp_f32_e32 v134, v134
	v_sub_f32_e32 v145, v145, v118
	v_exp_f32_e32 v145, v145
	v_sub_f32_e32 v144, v144, v118
	v_exp_f32_e32 v144, v144
	v_sub_f32_e32 v133, v133, v118
	v_add_f32_e32 v135, 0, v119
	v_exp_f32_e32 v133, v133
	v_sub_f32_e32 v132, v132, v118
	v_add_f32_e32 v135, v134, v135
	v_exp_f32_e32 v132, v132
	v_sub_f32_e32 v117, v117, v118
	v_add_f32_e32 v135, v145, v135
	v_exp_f32_e32 v117, v117
	v_sub_f32_e32 v116, v116, v118
	v_add_f32_e32 v135, v144, v135
	v_exp_f32_e32 v116, v116
	v_add_f32_e32 v135, v133, v135
	v_add_f32_e32 v135, v132, v135
	v_add_f32_e32 v135, v117, v135
	s_lshl_b32 s16, s46, 9
	v_add_f32_e32 v118, v116, v135
	v_cvt_pk_bf16_f32 v167, v117, v116
	v_mul_u32_u24_e32 v116, 0x44, v149
	s_add_i32 s72, s71, s16
	v_lshlrev_b32_e32 v116, 1, v116
	v_lshlrev_b32_e32 v117, 1, v150
	v_add3_u32 v116, s72, v116, v117
	v_cvt_pk_bf16_f32 v161, v153, v155
	v_cvt_pk_bf16_f32 v162, v156, v157
	v_add_u32_e32 v155, 0x4000, v116
	v_add_u32_e32 v156, 0x4800, v116
	v_cvt_pk_bf16_f32 v160, v151, v152
	v_cvt_pk_bf16_f32 v163, v158, v159
	v_cvt_pk_bf16_f32 v164, v119, v134
	v_cvt_pk_bf16_f32 v166, v133, v132
	ds_read2_b64 v[132:135], v155 offset1:4
	ds_read2_b64 v[150:153], v156 offset0:16 offset1:20
	v_add_u32_e32 v157, 0x5000, v116
	v_add_u32_e32 v158, 0x5800, v116
	ds_read2_b64 v[168:171], v157 offset0:32 offset1:36
	ds_read2_b64 v[172:175], v158 offset0:48 offset1:52
	v_add_f32_e32 v197, v197, v118
	v_cvt_pk_bf16_f32 v165, v145, v144
	v_add_u32_e32 v159, v147, v146
	v_add_u32_e32 v176, v148, v146
	ds_read_b128 v[198:201], v159 offset:4096
	ds_read_b128 v[242:245], v159 offset:6144
	ds_read_b128 v[246:249], v176 offset:4096
	s_setprio 1
	s_waitcnt lgkmcnt(6)
	v_mfma_f32_16x16x32_bf16 v[116:119], v[132:135], v[160:163], v[112:115]
	v_mfma_f32_16x16x32_bf16 v[132:135], v[132:135], v[164:167], v[124:127]
	s_waitcnt lgkmcnt(5)
	v_mfma_f32_16x16x32_bf16 v[112:115], v[150:153], v[160:163], v[104:107]
	v_mfma_f32_16x16x32_bf16 v[128:131], v[150:153], v[164:167], v[128:131]
	s_waitcnt lgkmcnt(4)
	v_mfma_f32_16x16x32_bf16 v[108:111], v[168:171], v[160:163], v[108:111]
	v_mfma_f32_16x16x32_bf16 v[124:127], v[168:171], v[164:167], v[136:139]
	s_waitcnt lgkmcnt(3)
	v_mfma_f32_16x16x32_bf16 v[104:107], v[172:175], v[160:163], v[120:123]
	v_mfma_f32_16x16x32_bf16 v[120:123], v[172:175], v[164:167], v[140:143]
	s_setprio 0
	s_nop 1
	v_add_u32_e32 v140, v147, v146
	v_add_u32_e32 v148, v148, v146
	ds_read_b128 v[148:151], v148 offset:6144
	v_add_u32_e32 v251, 0xa00, v154
	ds_read2_b32 v[202:203], v154 offset0:31 offset1:32
	ds_read2_b32 v[204:205], v154 offset0:29 offset1:30
	ds_read2_b32 v[206:207], v154 offset0:15 offset1:16
	ds_read2_b32 v[208:209], v154 offset0:13 offset1:14
	ds_read2_b32 v[210:211], v251 offset0:31 offset1:32
	ds_read2_b32 v[236:237], v251 offset0:29 offset1:30
	ds_read2_b32 v[238:239], v251 offset0:15 offset1:16
	ds_read2_b32 v[240:241], v251 offset0:13 offset1:14
	s_setprio 1
	s_waitcnt lgkmcnt(11)
	v_mfma_f32_16x16x32_bf16 v[160:163], v[198:201], v[0:3], 0
	v_mfma_f32_16x16x32_bf16 v[136:139], v[198:201], v[8:11], 0
	s_waitcnt lgkmcnt(10)
	v_mfma_f32_16x16x32_bf16 v[168:171], v[242:245], v[8:11], 0
	v_mfma_f32_16x16x32_bf16 v[164:167], v[242:245], v[0:3], 0
	s_waitcnt lgkmcnt(9)
	v_mfma_f32_16x16x32_bf16 v[160:163], v[246:249], v[4:7], v[160:163]
	v_mfma_f32_16x16x32_bf16 v[140:143], v[246:249], v[12:15], v[136:139]
	s_waitcnt lgkmcnt(8)
	v_mfma_f32_16x16x32_bf16 v[136:139], v[148:151], v[12:15], v[168:171]
	v_mfma_f32_16x16x32_bf16 v[164:167], v[148:151], v[4:7], v[164:167]
	s_setprio 0
	s_waitcnt lgkmcnt(7)
	s_nop 1
	v_fmamk_f32 v160, v160, 0x3e38aa3b, v203
	v_fmamk_f32 v150, v161, 0x3e38aa3b, v202
	s_waitcnt lgkmcnt(6)
	v_fmamk_f32 v159, v162, 0x3e38aa3b, v205
	v_fmamk_f32 v148, v163, 0x3e38aa3b, v204
	s_waitcnt lgkmcnt(5)
	v_fmamk_f32 v151, v164, 0x3e38aa3b, v207
	v_fmamk_f32 v146, v165, 0x3e38aa3b, v206
	s_waitcnt lgkmcnt(4)
	v_fmamk_f32 v145, v166, 0x3e38aa3b, v209
	v_fmamk_f32 v144, v167, 0x3e38aa3b, v208
	ds_read2_b64 v[202:205], v155 offset0:8 offset1:12
	ds_read2_b64 v[206:209], v156 offset0:24 offset1:28
	ds_read2_b64 v[242:245], v157 offset0:40 offset1:44
	ds_read2_b64 v[246:249], v158 offset0:56 offset1:60
	v_max3_f32 v147, v160, v150, v159
	v_max3_f32 v149, v148, v151, v146
	v_max_f32_e32 v152, v145, v144
	v_max3_f32 v147, v152, v147, v149
	v_add_f32_e32 v149, 0x41000000, v192
	v_cmp_gt_f32_e32 vcc, v147, v149
	s_cbranch_vccz .LBB0_387
	ds_bpermute_b32 v149, v233, v147
	v_max_f32_e32 v147, v147, v147
	v_mov_b32_e32 v153, v193
	s_waitcnt lgkmcnt(0)
	v_max_f32_e32 v149, v149, v149
	v_max_f32_e32 v147, v147, v149
	ds_bpermute_b32 v149, v234, v147
	s_waitcnt lgkmcnt(0)
	v_max3_f32 v152, v192, v147, v149
	v_sub_f32_e32 v147, v192, v152
	v_exp_f32_e32 v162, v147
	v_mov_b64_e32 v[192:193], v[152:153]
	v_mul_f32_e32 v196, v196, v162
	v_pk_mul_f32 v[118:119], v[118:119], v[162:163] op_sel_hi:[1,0]
	v_pk_mul_f32 v[116:117], v[116:117], v[162:163] op_sel_hi:[1,0]
	v_pk_mul_f32 v[114:115], v[114:115], v[162:163] op_sel_hi:[1,0]
	v_pk_mul_f32 v[112:113], v[112:113], v[162:163] op_sel_hi:[1,0]
	v_pk_mul_f32 v[110:111], v[110:111], v[162:163] op_sel_hi:[1,0]
	v_pk_mul_f32 v[108:109], v[108:109], v[162:163] op_sel_hi:[1,0]
	v_pk_mul_f32 v[106:107], v[106:107], v[162:163] op_sel_hi:[1,0]
	v_pk_mul_f32 v[104:105], v[104:105], v[162:163] op_sel_hi:[1,0]
	s_branch .LBB0_388

; template <int MODE>
; __device__ __forceinline__ void nsa_compute(int cur, int buf, int t, int hl, u64 mymask, const bf16x8 (&Qf)[2][2], f32x4 (&O)[4][2], float (&m)[2], float (&l)[2],
;                                             const float (&inv)[2], float* impw, char* lds) {
;     ...
; #pragma unroll
;     for (int ks = 0; ks < 2; ++ks)
; #pragma unroll
;       for (int kk = 0; kk < 2; ++kk) kfr[ks][kk] = *(const bf16x8*)(kt + (32 * s2 + 16 * kk + fr) * 128 + (((ks * 4 + fq) ^ (fr & 7)) << 4));
;     __builtin_amdgcn_s_setprio(1);
; #pragma unroll
;     for (int ks = 0; ks < 2; ++ks)
; #pragma unroll
;       for (int kk = 0; kk < 2; ++kk)
; #pragma unroll
;         for (int r = 0; r < 2; ++r) S[kk][r] = mfma16(kfr[ks][kk], Qf[r][ks], S[kk][r]);
;     __builtin_amdgcn_s_setprio(0);
;     bf16x8 Pf[2];
;     float g1s[2] = {0.f, 0.f}, p3s[2] = {0.f, 0.f};
; #pragma unroll
;     for (int r = 0; r < 2; ++r) {
;       float sv[2][4];
; #pragma unroll
;       for (int kk = 0; kk < 2; ++kk)
; #pragma unroll
;         for (int e = 0; e < 4; ++e) {
;     ...
;         const float me = (MODE == 2) ? (selok ? m[r] : __builtin_inff()) : m[r];
;         float ps = 0.f;
; #pragma unroll
;         for (int kk = 0; kk < 2; ++kk)
; #pragma unroll
;           for (int e = 0; e < 4; ++e) { pv[kk][e] = __builtin_amdgcn_exp2f(sv[kk][e] - me); ps += pv[kk][e]; }
;         l[r] += ps;
;       }
;       if (MODE != 0) {
;         const unsigned w0 = pk2(pv[0][0], pv[0][1]), w1 = pk2(pv[0][2], pv[0][3]), w2 = pk2(pv[1][0], pv[1][1]), w3 = pk2(pv[1][2], pv[1][3]);
;         u32x4 pw; pw.x = w0; pw.y = w1; pw.z = w2; pw.w = w3;
;         Pf[r] = __builtin_bit_cast(bf16x8, pw);
;       }
;     }
;     if (MODE != 0) {
;       bf16x8 vfr[4];
; #pragma unroll
;       for (int df = 0; df < 4; ++df) {
;         const bf16x4 va = *(const bf16x4*)(vt + (df * 16 + fr) * 68 + 32 * s2 + 4 * fq);
;         const bf16x4 vb = *(const bf16x4*)(vt + (df * 16 + fr) * 68 + 32 * s2 + 16 + 4 * fq);
;         bf16x8 vf; vf[0] = va[0]; vf[1] = va[1]; vf[2] = va[2]; vf[3] = va[3]; vf[4] = vb[0]; vf[5] = vb[1]; vf[6] = vb[2]; vf[7] = vb[3];
;         vfr[df] = vf;
;       }
;       __builtin_amdgcn_s_setprio(1);
; #pragma unroll
;       for (int df = 0; df < 4; ++df)
; #pragma unroll
;         for (int r = 0; r < 2; ++r) O[df][r] = mfma16(vfr[df], Pf[r], O[df][r]);
;       __builtin_amdgcn_s_setprio(0);
.LBB0_442:
	v_cndmask_b32_e64 v74, v74, v228, s[36:37]
	v_sub_f32_e32 v75, v81, v74
	v_exp_f32_e32 v75, v75
	v_sub_f32_e32 v80, v80, v74
	v_exp_f32_e32 v80, v80
	v_sub_f32_e32 v78, v78, v74
	v_exp_f32_e32 v78, v78
	v_sub_f32_e32 v81, v82, v74
	v_exp_f32_e32 v81, v81
	v_sub_f32_e32 v77, v77, v74
	v_add_f32_e32 v79, 0, v75
	v_exp_f32_e32 v77, v77
	v_sub_f32_e32 v76, v76, v74
	v_add_f32_e32 v79, v80, v79
	v_exp_f32_e32 v76, v76
	v_sub_f32_e32 v73, v73, v74
	v_add_f32_e32 v79, v78, v79
	v_exp_f32_e32 v73, v73
	v_sub_f32_e32 v72, v72, v74
	v_add_f32_e32 v79, v81, v79
	v_exp_f32_e32 v72, v72
	v_add_f32_e32 v79, v77, v79
	v_add_f32_e32 v79, v76, v79
	v_add_f32_e32 v79, v73, v79
	s_lshl_b32 s17, s74, 9
	v_add_f32_e32 v74, v72, v79
	v_cvt_pk_bf16_f32 v101, v73, v72
	v_mul_u32_u24_e32 v72, 0x44, v94
	s_add_i32 s71, s63, s17
	v_lshlrev_b32_e32 v72, 1, v72
	v_lshlrev_b32_e32 v73, 1, v95
	v_add3_u32 v72, s71, v72, v73
	v_add_u32_e32 v94, 0x4000, v72
	v_cvt_pk_bf16_f32 v87, v87, v88
	v_cvt_pk_bf16_f32 v88, v89, v96
	v_cvt_pk_bf16_f32 v89, v97, v84
	v_cvt_pk_bf16_f32 v99, v78, v81
	v_cvt_pk_bf16_f32 v100, v77, v76
	v_add_u32_e32 v95, 0x4800, v72
	v_add_u32_e32 v96, 0x5000, v72
	v_add_u32_e32 v97, 0x5800, v72
	v_cvt_pk_bf16_f32 v86, v85, v86
	v_add_f32_e32 v191, v191, v74
	v_cvt_pk_bf16_f32 v98, v75, v80
	v_add_u32_e32 v110, v92, v91
	v_add_u32_e32 v111, v93, v91
	ds_read_b128 v[112:115], v110 offset:4096
	ds_read_b128 v[116:119], v110 offset:6144
	ds_read_b128 v[192:195], v111 offset:4096
	ds_read_b128 v[198:201], v111 offset:6144
	s_setprio 1
	s_waitcnt lgkmcnt(7)
	v_mfma_f32_16x16x32_bf16 v[72:75], v[150:153], v[86:89], v[16:19]
	v_mfma_f32_16x16x32_bf16 v[80:83], v[150:153], v[98:101], v[20:23]
	s_waitcnt lgkmcnt(6)
	v_mfma_f32_16x16x32_bf16 v[24:27], v[154:157], v[86:89], v[24:27]
	v_mfma_f32_16x16x32_bf16 v[76:79], v[154:157], v[98:101], v[28:31]
	s_waitcnt lgkmcnt(5)
	v_mfma_f32_16x16x32_bf16 v[20:23], v[168:171], v[86:89], v[32:35]
	v_mfma_f32_16x16x32_bf16 v[32:35], v[168:171], v[98:101], v[36:39]
	s_waitcnt lgkmcnt(4)
	v_mfma_f32_16x16x32_bf16 v[16:19], v[172:175], v[86:89], v[40:43]
	v_mfma_f32_16x16x32_bf16 v[28:31], v[172:175], v[98:101], v[44:47]
	s_setprio 0
	s_nop 0
	v_add_u32_e32 v40, v92, v91
	v_add_u32_e32 v84, v93, v91
	v_add_u32_e32 v251, 0x8400, v90
	v_add_u32_e32 v250, 0xc500, v90
	ds_read2_b32 v[138:139], v251 offset0:31 offset1:32
	ds_read2_b32 v[140:141], v251 offset0:29 offset1:30
	ds_read2_b32 v[142:143], v251 offset0:15 offset1:16
	ds_read2_b32 v[148:149], v251 offset0:13 offset1:14
	ds_read2_b32 v[150:151], v250 offset0:31 offset1:32
	ds_read2_b32 v[152:153], v250 offset0:29 offset1:30
	ds_read2_b32 v[154:155], v250 offset0:15 offset1:16
	ds_read2_b32 v[156:157], v250 offset0:13 offset1:14
	s_setprio 1
	s_waitcnt lgkmcnt(11)
	v_mfma_f32_16x16x32_bf16 v[98:101], v[112:115], v[0:3], 0
	v_mfma_f32_16x16x32_bf16 v[36:39], v[112:115], v[8:11], 0
	s_waitcnt lgkmcnt(10)
	v_mfma_f32_16x16x32_bf16 v[106:109], v[116:119], v[8:11], 0
	v_mfma_f32_16x16x32_bf16 v[102:105], v[116:119], v[0:3], 0
	s_waitcnt lgkmcnt(9)
	v_mfma_f32_16x16x32_bf16 v[40:43], v[192:195], v[12:15], v[36:39]
	s_waitcnt lgkmcnt(8)
	v_mfma_f32_16x16x32_bf16 v[36:39], v[198:201], v[12:15], v[106:109]
	v_mfma_f32_16x16x32_bf16 v[98:101], v[192:195], v[4:7], v[98:101]
	v_mfma_f32_16x16x32_bf16 v[102:105], v[198:201], v[4:7], v[102:105]
	s_setprio 0
	s_waitcnt lgkmcnt(7)
	s_nop 4
	v_fmamk_f32 v91, v98, 0x3e38aa3b, v139
	v_fmamk_f32 v84, v99, 0x3e38aa3b, v138
	s_waitcnt lgkmcnt(6)
	v_fmamk_f32 v85, v100, 0x3e38aa3b, v141
	v_fmamk_f32 v46, v101, 0x3e38aa3b, v140
	s_waitcnt lgkmcnt(5)
	v_fmamk_f32 v45, v102, 0x3e38aa3b, v143
	v_fmamk_f32 v44, v103, 0x3e38aa3b, v142
	v_max3_f32 v47, v91, v84, v85
	s_waitcnt lgkmcnt(4)
	v_fmamk_f32 v92, v104, 0x3e38aa3b, v149
	v_fmamk_f32 v86, v105, 0x3e38aa3b, v148
	ds_read2_b64 v[138:141], v94 offset0:8 offset1:12
	ds_read2_b64 v[168:171], v95 offset0:24 offset1:28
	ds_read2_b64 v[108:111], v96 offset0:40 offset1:44
	ds_read2_b64 v[112:115], v97 offset0:56 offset1:60
	v_max3_f32 v87, v46, v45, v44
	v_max_f32_e32 v88, v92, v86
	v_max3_f32 v47, v88, v47, v87
	v_cndmask_b32_e64 v47, v47, v225, s[36:37]
	v_add_f32_e32 v87, 0x41000000, v188
	v_cmp_gt_f32_e32 vcc, v47, v87
	s_cbranch_vccz .LBB0_444
	ds_bpermute_b32 v87, v233, v47
	v_max_f32_e32 v47, v47, v47
	v_mov_b32_e32 v89, v189
	s_waitcnt lgkmcnt(0)
	v_max_f32_e32 v87, v87, v87
	v_max_f32_e32 v47, v47, v87
	ds_bpermute_b32 v87, v234, v47
	s_waitcnt lgkmcnt(0)
	v_max3_f32 v88, v188, v47, v87
	v_sub_f32_e32 v47, v188, v88
	v_exp_f32_e32 v98, v47
	v_mov_b64_e32 v[188:189], v[88:89]
	v_mul_f32_e32 v190, v190, v98
	v_pk_mul_f32 v[74:75], v[74:75], v[98:99] op_sel_hi:[1,0]
	v_pk_mul_f32 v[72:73], v[72:73], v[98:99] op_sel_hi:[1,0]
	v_pk_mul_f32 v[26:27], v[26:27], v[98:99] op_sel_hi:[1,0]
	v_pk_mul_f32 v[24:25], v[24:25], v[98:99] op_sel_hi:[1,0]
	v_pk_mul_f32 v[22:23], v[22:23], v[98:99] op_sel_hi:[1,0]
	v_pk_mul_f32 v[20:21], v[20:21], v[98:99] op_sel_hi:[1,0]
	v_pk_mul_f32 v[18:19], v[18:19], v[98:99] op_sel_hi:[1,0]
	v_pk_mul_f32 v[16:17], v[16:17], v[98:99] op_sel_hi:[1,0]
	s_branch .LBB0_445

; template <int MODE>
; __device__ __forceinline__ void nsa_compute(int cur, int buf, int t, int hl, u64 mymask, const bf16x8 (&Qf)[2][2], f32x4 (&O)[4][2], float (&m)[2], float (&l)[2],
;                                             const float (&inv)[2], float* impw, char* lds) {
;     ...
; #pragma unroll
;     for (int ks = 0; ks < 2; ++ks)
; #pragma unroll
;       for (int kk = 0; kk < 2; ++kk) kfr[ks][kk] = *(const bf16x8*)(kt + (32 * s2 + 16 * kk + fr) * 128 + (((ks * 4 + fq) ^ (fr & 7)) << 4));
;     __builtin_amdgcn_s_setprio(1);
; #pragma unroll
;     for (int ks = 0; ks < 2; ++ks)
; #pragma unroll
;       for (int kk = 0; kk < 2; ++kk)
; #pragma unroll
;         for (int r = 0; r < 2; ++r) S[kk][r] = mfma16(kfr[ks][kk], Qf[r][ks], S[kk][r]);
;     __builtin_amdgcn_s_setprio(0);
;     bf16x8 Pf[2];
;     float g1s[2] = {0.f, 0.f}, p3s[2] = {0.f, 0.f};
; #pragma unroll
;     for (int r = 0; r < 2; ++r) {
;       float sv[2][4];
; #pragma unroll
;       for (int kk = 0; kk < 2; ++kk)
; #pragma unroll
;         for (int e = 0; e < 4; ++e) {
;     ...
;         const float me = (MODE == 2) ? (selok ? m[r] : __builtin_inff()) : m[r];
;         float ps = 0.f;
; #pragma unroll
;         for (int kk = 0; kk < 2; ++kk)
; #pragma unroll
;           for (int e = 0; e < 4; ++e) { pv[kk][e] = __builtin_amdgcn_exp2f(sv[kk][e] - me); ps += pv[kk][e]; }
;         l[r] += ps;
;       }
;       if (MODE != 0) {
;         const unsigned w0 = pk2(pv[0][0], pv[0][1]), w1 = pk2(pv[0][2], pv[0][3]), w2 = pk2(pv[1][0], pv[1][1]), w3 = pk2(pv[1][2], pv[1][3]);
;         u32x4 pw; pw.x = w0; pw.y = w1; pw.z = w2; pw.w = w3;
;         Pf[r] = __builtin_bit_cast(bf16x8, pw);
;       }
;     }
;     if (MODE != 0) {
;       bf16x8 vfr[4];
; #pragma unroll
;       for (int df = 0; df < 4; ++df) {
;         const bf16x4 va = *(const bf16x4*)(vt + (df * 16 + fr) * 68 + 32 * s2 + 4 * fq);
;         const bf16x4 vb = *(const bf16x4*)(vt + (df * 16 + fr) * 68 + 32 * s2 + 16 + 4 * fq);
;         bf16x8 vf; vf[0] = va[0]; vf[1] = va[1]; vf[2] = va[2]; vf[3] = va[3]; vf[4] = vb[0]; vf[5] = vb[1]; vf[6] = vb[2]; vf[7] = vb[3];
;         vfr[df] = vf;
;       }
;       __builtin_amdgcn_s_setprio(1);
; #pragma unroll
;       for (int df = 0; df < 4; ++df)
; #pragma unroll
;         for (int r = 0; r < 2; ++r) O[df][r] = mfma16(vfr[df], Pf[r], O[df][r]);
;       __builtin_amdgcn_s_setprio(0);
.LBB0_459:
	v_cndmask_b32_e64 v30, v30, v228, s[36:37]
	v_sub_f32_e32 v31, v47, v30
	v_exp_f32_e32 v31, v31
	v_sub_f32_e32 v46, v46, v30
	v_exp_f32_e32 v46, v46
	v_sub_f32_e32 v113, v113, v30
	v_exp_f32_e32 v113, v113
	v_sub_f32_e32 v112, v112, v30
	v_exp_f32_e32 v112, v112
	v_sub_f32_e32 v45, v45, v30
	v_add_f32_e32 v47, 0, v31
	v_exp_f32_e32 v45, v45
	v_sub_f32_e32 v44, v44, v30
	v_add_f32_e32 v47, v46, v47
	v_exp_f32_e32 v44, v44
	v_sub_f32_e32 v29, v29, v30
	v_add_f32_e32 v47, v113, v47
	v_exp_f32_e32 v29, v29
	v_sub_f32_e32 v28, v28, v30
	v_add_f32_e32 v47, v112, v47
	v_exp_f32_e32 v28, v28
	v_add_f32_e32 v47, v45, v47
	v_add_f32_e32 v47, v44, v47
	v_add_f32_e32 v47, v29, v47
	s_lshl_b32 s16, s74, 9
	v_add_f32_e32 v30, v28, v47
	v_cvt_pk_bf16_f32 v135, v29, v28
	v_mul_u32_u24_e32 v28, 0x44, v117
	s_add_i32 s73, s72, s16
	v_lshlrev_b32_e32 v28, 1, v28
	v_lshlrev_b32_e32 v29, 1, v118
	v_add3_u32 v28, s73, v28, v29
	v_cvt_pk_bf16_f32 v129, v121, v123
	v_cvt_pk_bf16_f32 v130, v124, v125
	v_add_u32_e32 v123, 0x4000, v28
	v_add_u32_e32 v124, 0x4800, v28
	v_cvt_pk_bf16_f32 v128, v119, v120
	v_cvt_pk_bf16_f32 v131, v126, v127
	v_cvt_pk_bf16_f32 v132, v31, v46
	v_cvt_pk_bf16_f32 v134, v45, v44
	v_add_u32_e32 v125, 0x5000, v28
	v_add_u32_e32 v126, 0x5800, v28
	v_add_f32_e32 v147, v147, v30
	v_cvt_pk_bf16_f32 v133, v113, v112
	v_add_u32_e32 v120, v115, v114
	v_add_u32_e32 v121, v116, v114
	ds_read_b128 v[140:143], v120 offset:4096
	ds_read_b128 v[148:151], v120 offset:6144
	ds_read_b128 v[236:239], v121 offset:4096
	ds_read_b128 v[240:243], v121 offset:6144
	s_setprio 1
	s_waitcnt lgkmcnt(7)
	v_mfma_f32_16x16x32_bf16 v[28:31], v[192:195], v[128:131], v[24:27]
	v_mfma_f32_16x16x32_bf16 v[44:47], v[192:195], v[132:135], v[36:39]
	s_waitcnt lgkmcnt(6)
	v_mfma_f32_16x16x32_bf16 v[24:27], v[198:201], v[128:131], v[16:19]
	v_mfma_f32_16x16x32_bf16 v[40:43], v[198:201], v[132:135], v[40:43]
	s_waitcnt lgkmcnt(5)
	v_mfma_f32_16x16x32_bf16 v[20:23], v[202:205], v[128:131], v[20:23]
	v_mfma_f32_16x16x32_bf16 v[36:39], v[202:205], v[132:135], v[104:107]
	s_waitcnt lgkmcnt(4)
	v_mfma_f32_16x16x32_bf16 v[16:19], v[206:209], v[128:131], v[32:35]
	v_mfma_f32_16x16x32_bf16 v[32:35], v[206:209], v[132:135], v[108:111]
	s_setprio 0
	s_nop 1
	v_add_u32_e32 v108, v115, v114
	v_add_u32_e32 v116, v116, v114
	v_add_u32_e32 v251, 0x8400, v122
	v_add_u32_e32 v250, 0xc500, v122
	ds_read2_b32 v[152:153], v251 offset0:31 offset1:32
	ds_read2_b32 v[154:155], v251 offset0:29 offset1:30
	ds_read2_b32 v[156:157], v251 offset0:15 offset1:16
	ds_read2_b32 v[168:169], v251 offset0:13 offset1:14
	ds_read2_b32 v[170:171], v250 offset0:31 offset1:32
	ds_read2_b32 v[172:173], v250 offset0:29 offset1:30
	ds_read2_b32 v[174:175], v250 offset0:15 offset1:16
	ds_read2_b32 v[192:193], v250 offset0:13 offset1:14
	s_setprio 1
	s_waitcnt lgkmcnt(11)
	v_mfma_f32_16x16x32_bf16 v[128:131], v[140:143], v[0:3], 0
	v_mfma_f32_16x16x32_bf16 v[104:107], v[140:143], v[8:11], 0
	s_waitcnt lgkmcnt(10)
	v_mfma_f32_16x16x32_bf16 v[136:139], v[148:151], v[8:11], 0
	v_mfma_f32_16x16x32_bf16 v[132:135], v[148:151], v[0:3], 0
	s_waitcnt lgkmcnt(9)
	v_mfma_f32_16x16x32_bf16 v[128:131], v[236:239], v[4:7], v[128:131]
	v_mfma_f32_16x16x32_bf16 v[108:111], v[236:239], v[12:15], v[104:107]
	s_waitcnt lgkmcnt(8)
	v_mfma_f32_16x16x32_bf16 v[104:107], v[240:243], v[12:15], v[136:139]
	v_mfma_f32_16x16x32_bf16 v[132:135], v[240:243], v[4:7], v[132:135]
	s_setprio 0
	s_waitcnt lgkmcnt(7)
	s_nop 1
	v_fmamk_f32 v127, v128, 0x3e38aa3b, v153
	v_fmamk_f32 v116, v129, 0x3e38aa3b, v152
	s_waitcnt lgkmcnt(6)
	v_fmamk_f32 v117, v130, 0x3e38aa3b, v155
	v_fmamk_f32 v114, v131, 0x3e38aa3b, v154
	s_waitcnt lgkmcnt(5)
	v_fmamk_f32 v113, v132, 0x3e38aa3b, v157
	v_fmamk_f32 v112, v133, 0x3e38aa3b, v156
	v_max3_f32 v115, v127, v116, v117
	s_waitcnt lgkmcnt(4)
	v_fmamk_f32 v128, v134, 0x3e38aa3b, v169
	v_fmamk_f32 v118, v135, 0x3e38aa3b, v168
	ds_read2_b64 v[152:155], v123 offset0:8 offset1:12
	ds_read2_b64 v[198:201], v124 offset0:24 offset1:28
	ds_read2_b64 v[202:205], v125 offset0:40 offset1:44
	ds_read2_b64 v[206:209], v126 offset0:56 offset1:60
	v_max3_f32 v119, v114, v113, v112
	v_max_f32_e32 v120, v128, v118
	v_max3_f32 v115, v120, v115, v119
	v_cndmask_b32_e64 v115, v115, v225, s[36:37]
	v_add_f32_e32 v119, 0x41000000, v188
	v_cmp_gt_f32_e32 vcc, v115, v119
	s_cbranch_vccz .LBB0_461
	ds_bpermute_b32 v119, v233, v115
	v_max_f32_e32 v115, v115, v115
	v_mov_b32_e32 v121, v189
	s_waitcnt lgkmcnt(0)
	v_max_f32_e32 v119, v119, v119
	v_max_f32_e32 v115, v115, v119
	ds_bpermute_b32 v119, v234, v115
	s_waitcnt lgkmcnt(0)
	v_max3_f32 v120, v188, v115, v119
	v_sub_f32_e32 v115, v188, v120
	v_exp_f32_e32 v130, v115
	v_mov_b64_e32 v[188:189], v[120:121]
	v_mul_f32_e32 v146, v146, v130
	v_pk_mul_f32 v[30:31], v[30:31], v[130:131] op_sel_hi:[1,0]
	v_pk_mul_f32 v[28:29], v[28:29], v[130:131] op_sel_hi:[1,0]
	v_pk_mul_f32 v[26:27], v[26:27], v[130:131] op_sel_hi:[1,0]
	v_pk_mul_f32 v[24:25], v[24:25], v[130:131] op_sel_hi:[1,0]
	v_pk_mul_f32 v[22:23], v[22:23], v[130:131] op_sel_hi:[1,0]
	v_pk_mul_f32 v[20:21], v[20:21], v[130:131] op_sel_hi:[1,0]
	v_pk_mul_f32 v[18:19], v[18:19], v[130:131] op_sel_hi:[1,0]
	v_pk_mul_f32 v[16:17], v[16:17], v[130:131] op_sel_hi:[1,0]
	s_branch .LBB0_462
